# attention: counted lgkmcnt waits per MFMA in the P.V segment + one static s_setprio 1 for waves 4-7
# baseline (speedup 1.0000x reference)
; #define LAS __attribute__((address_space(3)))
; __device__ __forceinline__ void attn_mfma(LAS unsigned char* lds, int layer, int G, const int wave_s) {
;     ...
;     const int r32 = lane & 31, hi = lane >> 5, h = wave, kv = h >> 2;
;     const float sk = Pp->in[18][layer * NH + h] * LOG2E;
;     const unsigned lbase = (unsigned)(uintptr_t)lds;
;     LAS float* al_l = (LAS float*)(lds + AT_SCR) + wave * 64; LAS float* li_l = al_l + 32;
;     LAS float* xa = (LAS float*)(lds + AT_XA); LAS float* xh = (LAS float*)(lds + AT_XH);
;     const int nunits = layer == DEPTH - 1 ? ML / 32 : MT / 32;
;     for (int unit = blockIdx.x; unit < nunits; unit += G) {
.Lcf_e:
	s_cmpk_ge_u32 s1, 0x100
	s_cbranch_scc0 .Lattn_prio_done
	s_setprio 1

; __device__ __forceinline__ int v_rd_base(int lane) { return ((lane & 3) << 3) | (((lane >> 2) & 3) << 6) | (((lane >> 4) & 1) << 5) | (((lane >> 5) & 1) << 8); }
; template <int OFF> __device__ __forceinline__ s16x4 tr_read(int vb) { s16x4 r; asm volatile("ds_read_b64_tr_b16 %0, %1 offset:%2" : "=&v"(r) : "v"(vb), "i"(OFF) : "memory"); return r; }
; template <int D0> __device__ __forceinline__ void pv_one4(f32x16& od, int vb, bf16x8 pa0, bf16x8 pa1, bf16x8 pa2, bf16x8 pa3) {
;     const s16x4 l0 = tr_read<v_rd_off(D0, 0, 0)>(vb), h0 = tr_read<v_rd_off(D0, 0, 1)>(vb), l1 = tr_read<v_rd_off(D0, 1, 0)>(vb), h1 = tr_read<v_rd_off(D0, 1, 1)>(vb);
;     const s16x4 l2 = tr_read<v_rd_off(D0, 2, 0)>(vb), h2 = tr_read<v_rd_off(D0, 2, 1)>(vb), l3 = tr_read<v_rd_off(D0, 3, 0)>(vb), h3 = tr_read<v_rd_off(D0, 3, 1)>(vb);
;     asm volatile("s_waitcnt lgkmcnt(0)" ::: "memory"); __builtin_amdgcn_sched_barrier(0);
;     ...
;     od = __builtin_amdgcn_mfma_f32_32x32x16_bf16(pa0, AT_PK(l0, h0), od, 0, 0, 0);
;     od = __builtin_amdgcn_mfma_f32_32x32x16_bf16(pa1, AT_PK(l1, h1), od, 0, 0, 0);
;     od = __builtin_amdgcn_mfma_f32_32x32x16_bf16(pa2, AT_PK(l2, h2), od, 0, 0, 0);
;     od = __builtin_amdgcn_mfma_f32_32x32x16_bf16(pa3, AT_PK(l3, h3), od, 0, 0, 0);
; __device__ __forceinline__ void attn_mfma(LAS unsigned char* lds, int layer, int G, const int wave_s) {
;     ...
;             { const int vb = (int)(lbase + bf * AT_BUF + 32768 + kv * 16384) + v_rd_base(lane);
;               pv_one4<0>(o[0], vb, pa0, pa1, pa2, pa3); pv_one4<1>(o[1], vb, pa0, pa1, pa2, pa3); pv_one4<2>(o[2], vb, pa0, pa1, pa2, pa3); pv_one4<3>(o[3], vb, pa0, pa1, pa2, pa3); }
;             if (i + 1 < NT) AT_SWRITE(bf ^ 1);
.LBB0_808:
	v_add_u32_e32 v85, s71, v191
	ds_read_b64_tr_b16 v[86:87], v85 offset:0
	ds_read_b64_tr_b16 v[88:89], v85 offset:0x800
	ds_read_b64_tr_b16 v[90:91], v85 offset:0x1000
	ds_read_b64_tr_b16 v[92:93], v85 offset:0x1800
	ds_read_b64_tr_b16 v[94:95], v85 offset:0x2000
	ds_read_b64_tr_b16 v[96:97], v85 offset:0x2800
	ds_read_b64_tr_b16 v[218:219], v85 offset:0x3000
	ds_read_b64_tr_b16 v[220:221], v85 offset:0x3800
	s_waitcnt lgkmcnt(6)
	s_nop 0
	v_mfma_f32_32x32x16_bf16 v[50:65], v[66:69], v[86:89], v[50:65]
	ds_read_b64_tr_b16 v[86:87], v85 offset:0x200
	ds_read_b64_tr_b16 v[88:89], v85 offset:0xa00
	s_waitcnt lgkmcnt(6)
	v_mfma_f32_32x32x16_bf16 v[50:65], v[70:73], v[90:93], v[50:65]
	ds_read_b64_tr_b16 v[90:91], v85 offset:0x1200
	ds_read_b64_tr_b16 v[92:93], v85 offset:0x1a00
	s_waitcnt lgkmcnt(6)
	v_mfma_f32_32x32x16_bf16 v[50:65], v[74:77], v[94:97], v[50:65]
	ds_read_b64_tr_b16 v[94:95], v85 offset:0x2200
	ds_read_b64_tr_b16 v[96:97], v85 offset:0x2a00
	s_waitcnt lgkmcnt(6)
	v_mfma_f32_32x32x16_bf16 v[50:65], v[78:81], v[218:221], v[50:65]
	ds_read_b64_tr_b16 v[218:219], v85 offset:0x3200
	ds_read_b64_tr_b16 v[220:221], v85 offset:0x3a00
	s_waitcnt lgkmcnt(6)
	v_mfma_f32_32x32x16_bf16 v[34:49], v[66:69], v[86:89], v[34:49]
	ds_read_b64_tr_b16 v[86:87], v85 offset:0x400
	ds_read_b64_tr_b16 v[88:89], v85 offset:0xc00
	s_waitcnt lgkmcnt(6)
	v_mfma_f32_32x32x16_bf16 v[34:49], v[70:73], v[90:93], v[34:49]
	ds_read_b64_tr_b16 v[90:91], v85 offset:0x1400
	ds_read_b64_tr_b16 v[92:93], v85 offset:0x1c00
	s_waitcnt lgkmcnt(6)
	v_mfma_f32_32x32x16_bf16 v[34:49], v[74:77], v[94:97], v[34:49]
	ds_read_b64_tr_b16 v[94:95], v85 offset:0x2400
	ds_read_b64_tr_b16 v[96:97], v85 offset:0x2c00
	s_waitcnt lgkmcnt(6)
	v_mfma_f32_32x32x16_bf16 v[34:49], v[78:81], v[218:221], v[34:49]
	ds_read_b64_tr_b16 v[218:219], v85 offset:0x3400
	ds_read_b64_tr_b16 v[220:221], v85 offset:0x3c00
	s_waitcnt lgkmcnt(6)
	v_mfma_f32_32x32x16_bf16 v[18:33], v[66:69], v[86:89], v[18:33]
	ds_read_b64_tr_b16 v[86:87], v85 offset:0x600
	ds_read_b64_tr_b16 v[88:89], v85 offset:0xe00
	s_waitcnt lgkmcnt(6)
	v_mfma_f32_32x32x16_bf16 v[18:33], v[70:73], v[90:93], v[18:33]
	ds_read_b64_tr_b16 v[90:91], v85 offset:0x1600
	ds_read_b64_tr_b16 v[92:93], v85 offset:0x1e00
	s_waitcnt lgkmcnt(6)
	v_mfma_f32_32x32x16_bf16 v[18:33], v[74:77], v[94:97], v[18:33]
	ds_read_b64_tr_b16 v[94:95], v85 offset:0x2600
	ds_read_b64_tr_b16 v[96:97], v85 offset:0x2e00
	s_waitcnt lgkmcnt(6)
	v_mfma_f32_32x32x16_bf16 v[18:33], v[78:81], v[218:221], v[18:33]
	ds_read_b64_tr_b16 v[218:219], v85 offset:0x3600
	ds_read_b64_tr_b16 v[220:221], v85 offset:0x3e00
	s_waitcnt lgkmcnt(6)
	v_mfma_f32_32x32x16_bf16 v[2:17], v[66:69], v[86:89], v[2:17]
	s_andn2_b64 vcc, exec, s[54:55]
	s_waitcnt lgkmcnt(4)
	v_mfma_f32_32x32x16_bf16 v[2:17], v[70:73], v[90:93], v[2:17]
	s_waitcnt lgkmcnt(2)
	v_mfma_f32_32x32x16_bf16 v[2:17], v[74:77], v[94:97], v[2:17]
	s_waitcnt lgkmcnt(0)
	v_mfma_f32_32x32x16_bf16 v[2:17], v[78:81], v[218:221], v[2:17]
	s_cbranch_vccnz .LBB0_810
	s_xor_b32 s42, s71, 0x10000
	v_add_u32_e32 v67, s42, v233
	v_add_u32_e32 v66, s42, v234
	s_waitcnt vmcnt(7)
	ds_write_b128 v67, v[130:133]
	s_waitcnt vmcnt(6)
	ds_write_b128 v67, v[134:137] offset:16384
	s_waitcnt vmcnt(5)
	ds_write_b128 v66, v[138:141] offset:32768
	s_waitcnt vmcnt(4)
	ds_write_b128 v66, v[142:145] offset:49152
	s_waitcnt vmcnt(3)
	ds_write_b128 v67, v[146:149] offset:8192
	s_waitcnt vmcnt(2)
	ds_write_b128 v67, v[150:153] offset:24576
	s_waitcnt vmcnt(1)
	ds_write_b128 v66, v[154:157] offset:40960
	s_waitcnt vmcnt(0)
	ds_write_b128 v66, v[158:161] offset:57344

; #define FRESH_KP KP Pp; { unsigned long long ki_ = (unsigned long long)__builtin_amdgcn_kernarg_segment_ptr(); asm volatile("" : "+s"(ki_)); Pp = (KP)ki_; }
; template <int NLB> __device__ __forceinline__ void taps_items(int layer_lo, int nlayers, int first, int stride, const int wave_s) {
;     FRESH_IDS; FRESH_KP;
;     unsigned char* ws = Pp->ws;
;     { typedef float f32x16_ __attribute__((ext_vector_type(16)));
;       const int r32 = lane & 31, hi = lane >> 5;
;       constexpr int IT_L = 128 * (128 / NLB), IT_C = 128 * (8 / NLB), PER = IT_L + IT_C;
;       for (int it = first; it < nlayers * PER; it += stride) {
;           const int layer = layer_lo + it / PER; int r = it % PER; const bool isc = r >= IT_L; if (isc) r -= IT_L;
;           const int nb = r & 127, lc = r >> 7, L = isc ? CTX : SEQ; constexpr int nlb = NLB;
;           const bf16_t* arow = (const bf16_t*)(ws + WS_W3T) + ((size_t)layer * 4096 + nb * 32 + r32) * FH + hi * 8;
; __global__ void __launch_bounds__(NTHR, 2) mk_fwd(Params P) {
;     ...
;             attn_mfma(lds, layer, G, wave_s);
;             if (layer + 1 < DEPTH && (int)blockIdx.x >= MC / 32) { __syncthreads();
;                 taps_items<4>(layer + 1, 1, ((int)blockIdx.x - MC / 32) * NWAVES + wave_s, (G - MC / 32) * NWAVES, wave_s); }
.LBB0_826:
	s_setprio 0
	v_readlane_b32 s0, v254, 34
	v_readlane_b32 s1, v254, 35
	s_and_b64 s[0:1], s[0:1], s[44:45]
	s_andn2_b64 vcc, exec, s[0:1]
	s_waitcnt vmcnt(0) lgkmcnt(0)
	s_barrier
	s_cbranch_vccnz .LBB0_830
	v_readlane_b32 s0, v253, 2
	s_barrier
	v_mbcnt_lo_u32_b32 v0, -1, 0
	v_mbcnt_hi_u32_b32 v0, -1, v0
	s_mov_b64 s[36:37], s[94:95]
	v_readlane_b32 s0, v254, 39
	v_readlane_b32 s1, v254, 40
	s_andn2_b64 vcc, exec, s[0:1]
	s_cbranch_vccnz .LBB0_830
	s_load_dwordx2 s[28:29], s[36:37], 0xd8
	s_add_i32 s0, s76, 1
	v_and_b32_e32 v58, 31, v0
	v_ashrrev_i32_e32 v0, 5, v0
	v_lshlrev_b32_e32 v2, 3, v0
	s_waitcnt lgkmcnt(0)
	s_add_u32 s1, s28, 0x15e62000
	s_addc_u32 s10, s29, 0
	s_add_u32 s11, s28, 0x15c62000
	s_addc_u32 s15, s29, 0
	s_add_u32 s17, s28, 0x16062000
	s_addc_u32 s23, s29, 0
	s_add_u32 s25, s28, 0x160a6000
	s_addc_u32 s26, s29, 0
	v_ashrrev_i32_e32 v3, 31, v2
	s_add_u32 s28, s28, 0x260a6000
	s_addc_u32 s29, s29, 0
	v_lshlrev_b32_e32 v59, 2, v0
	v_lshlrev_b64 v[34:35], 1, v[2:3]
	v_readlane_b32 s35, v254, 38
	s_mov_b32 s49, 0x3fb8aa3b
